# phases 2/3: GEMM-first vs mixer-first workgroups chosen by blockIdx bit 4 (run 1)
# baseline (speedup 1.0000x reference)
;     __device__ bool next(int i, Unit& u) const { const int L = i * G + c; if (L >= 256) return false; u.pm = L; u.pn = L >> 3; return true; }
; #define GATES_ROUNDS(R0, R1) do { pg8::Gemm g{(const bf16_t*)(ws + WS_XB), (const bf16_t*)(ws + WS_WIN) + (size_t)NPROJ * 1024, 1024, 1024, 1024}; pg8::RoundRange S; S.base.init(MROWS, 2048, G, bx); S.r0 = (R0); S.r1 = (R1); \
;         Epi<EM_GATES> E{ws, nullptr, nullptr, nullptr, nullptr, 0, lds}; pg8::gemm_phase(lds, g, S, E, wave); } while (0)
;     __device__ bool next(int i, Unit& u) const {
;         const long L = (long)i * G + c; if (L >= nwg) return false;
;         int wgid = (int)L; { const int q = nwg / NXCD, r = nwg % NXCD, xcd = wgid % NXCD, off = wgid / NXCD; wgid = (xcd < r ? xcd * (q + 1) : r * (q + 1) + (xcd - r) * q) + off; }
;         const int nig = WGM * nN, gid = wgid / nig, fm = gid * WGM, gsz = (nM - fm) < WGM ? (nM - fm) : WGM;
;         u.pm = fm + ((wgid % nig) % gsz); u.pn = (wgid % nig) / gsz; return true;
;     }
;     __device__ bool next(int i, Unit& u) const { if (r0 + i >= r1) return false; return base.next(r0 + i, u); }
; __global__ void __launch_bounds__(NTHR, 2) fwd_megakernel(Prm P) {
;     ...
;     const bool local_ok = __builtin_amdgcn_readfirstlane((int)__hip_atomic_load((unsigned*)(ws + WS_CTL) + XL_BAD, __ATOMIC_RELAXED, __HIP_MEMORY_SCOPE_AGENT)) == 0 && IN(0) && IN(2);
;     ...
;     if (IN(2)) {
;         if (bx & 1) GATES_ROUNDS(0, 2);
.LBB0_653:
	v_mov_b32_e32 v0, 0x1f60a000
	global_load_dword v0, v0, s[92:93] offset:2048 sc1
	v_readlane_b32 s4, v255, 3
	v_readlane_b32 s5, v255, 4
	s_cmp_lt_i32 s4, 3
	s_cselect_b64 s[4:5], -1, 0
	s_and_b64 s[18:19], s[4:5], s[76:77]
	v_readlane_b32 s6, v255, 5
	v_readlane_b32 s7, v255, 6
	s_andn2_b64 vcc, exec, s[18:19]
	s_waitcnt vmcnt(0)
	v_readfirstlane_b32 s2, v0
	s_nop 1
	v_writelane_b32 v255, s2, 15
	s_cbranch_vccnz .LBB0_735
	s_bitcmp0_b32 s66, 4
	s_cselect_b64 s[20:21], -1, 0
	s_and_b64 vcc, exec, s[20:21]
	s_cbranch_vccnz .LBB0_680
	v_readlane_b32 s2, v255, 9
	v_mbcnt_lo_u32_b32 v0, -1, 0
	v_mbcnt_hi_u32_b32 v0, -1, v0
	s_cmpk_gt_i32 s66, 0x3ff
	s_nop 0
	v_add_u32_e32 v8, s2, v0
	s_cbranch_scc1 .LBB0_680
	s_ashr_i32 s2, s66, 31
	s_lshr_b32 s4, s2, 29
	s_add_i32 s7, s66, s4
	s_and_b32 s4, s7, -8
	s_sub_i32 s8, s66, s4
	s_cmp_gt_i32 s8, -1
	s_cbranch_scc0 .LBB0_658
	s_lshl_b32 s6, s8, 7
	s_cbranch_execz .LBB0_659
	s_branch .LBB0_660

;     __device__ bool next(int i, Unit& u) const { const int L = i * G + c; if (L >= 256) return false; u.pm = L; u.pn = L >> 3; return true; }
; #define GATES_ROUNDS(R0, R1) do { pg8::Gemm g{(const bf16_t*)(ws + WS_XB), (const bf16_t*)(ws + WS_WIN) + (size_t)NPROJ * 1024, 1024, 1024, 1024}; pg8::RoundRange S; S.base.init(MROWS, 2048, G, bx); S.r0 = (R0); S.r1 = (R1); \
;         Epi<EM_GATES> E{ws, nullptr, nullptr, nullptr, nullptr, 0, lds}; pg8::gemm_phase(lds, g, S, E, wave); } while (0)
;     __device__ bool next(int i, Unit& u) const {
;         const long L = (long)i * G + c; if (L >= nwg) return false;
;         int wgid = (int)L; { const int q = nwg / NXCD, r = nwg % NXCD, xcd = wgid % NXCD, off = wgid / NXCD; wgid = (xcd < r ? xcd * (q + 1) : r * (q + 1) + (xcd - r) * q) + off; }
;         const int nig = WGM * nN, gid = wgid / nig, fm = gid * WGM, gsz = (nM - fm) < WGM ? (nM - fm) : WGM;
;         u.pm = fm + ((wgid % nig) % gsz); u.pn = (wgid % nig) / gsz; return true;
;     }
;     __device__ bool next(int i, Unit& u) const { if (r0 + i >= r1) return false; return base.next(r0 + i, u); }
; __global__ void __launch_bounds__(NTHR, 2) fwd_megakernel(Prm P) {
;     ...
;     if (IN(3)) {
;         if (!(bx & 1)) GATES_ROUNDS(2, 4);
.LBB0_791:
	v_readlane_b32 s8, v255, 3
	s_cmp_lt_i32 s8, 4
	s_cselect_b64 s[6:7], -1, 0
	s_and_b64 s[4:5], s[6:7], s[4:5]
	v_readlane_b32 s9, v255, 4
	v_readlane_b32 s10, v255, 5
	v_readlane_b32 s11, v255, 6
	v_writelane_b32 v255, s4, 16
	s_andn2_b64 vcc, exec, s[4:5]
	s_nop 0
	v_writelane_b32 v255, s5, 17
	s_cbranch_vccnz .LBB0_870
	s_bitcmp1_b32 s66, 4
	s_cselect_b64 s[4:5], -1, 0
	v_writelane_b32 v255, s4, 18
	s_and_b64 vcc, exec, s[4:5]
	s_nop 0
	v_writelane_b32 v255, s5, 19
	s_cbranch_vccnz .LBB0_811
	v_readlane_b32 s4, v255, 1
	v_readlane_b32 s5, v255, 2
	s_ashr_i32 s5, s4, 31
	s_lshl_b64 s[6:7], s[4:5], 1
	s_ashr_i32 s5, s66, 31
	v_mbcnt_lo_u32_b32 v0, -1, 0
	v_mbcnt_hi_u32_b32 v0, -1, v0
	v_readlane_b32 s2, v255, 9
	s_add_u32 s6, s6, s66
	s_addc_u32 s7, s7, s5
	v_add_u32_e32 v14, s2, v0
	v_mov_b64_e32 v[0:1], 0x3ff
	v_cmp_gt_i64_e32 vcc, s[6:7], v[0:1]
	s_cbranch_vccnz .LBB0_811
	s_ashr_i32 s2, s6, 31
	s_lshr_b32 s2, s2, 29
	s_add_i32 s8, s6, s2
	s_and_b32 s2, s8, -8
	s_sub_i32 s2, s6, s2
	s_cmp_gt_i32 s2, -1
	s_cbranch_scc0 .LBB0_796
	s_lshl_b32 s9, s2, 7
	s_ashr_i32 s6, s8, 3
	s_cbranch_execz .LBB0_797
	s_branch .LBB0_798
